# v20 + attention loop row sums via 2-wide v_pk_add_f32 chain (17 instead of 32 VALU per step)
# baseline (speedup 1.0000x reference)
.LBB0_375:
	v_lshl_add_u32 v154, s60, 14, v241
	ds_read_b64_tr_b16 v[150:151], v154 offset:24576
	ds_read_b64_tr_b16 v[152:153], v154 offset:25088
	v_pk_add_f32 v[250:251], v[82:83], v[84:85]
	v_pk_add_f32 v[250:251], v[250:251], v[86:87]
	v_cvt_pk_bf16_f32 v174, v82, v83
	v_cvt_pk_bf16_f32 v175, v84, v85
	s_waitcnt lgkmcnt(9)
	v_mfma_f32_32x32x16_bf16 v[114:129], v[102:105], v[190:193], 0
	ds_read_b64_tr_b16 v[82:83], v154 offset:28672
	ds_read_b64_tr_b16 v[84:85], v154 offset:29184
	v_pk_add_f32 v[250:251], v[250:251], v[88:89]
	v_pk_add_f32 v[250:251], v[250:251], v[90:91]
	s_waitcnt lgkmcnt(10)
	v_mfma_f32_32x32x16_bf16 v[98:113], v[98:101], v[190:193], 0
	v_cvt_pk_bf16_f32 v176, v86, v87
	v_cvt_pk_bf16_f32 v177, v88, v89
	ds_read_b64_tr_b16 v[86:87], v154 offset:32768
	ds_read_b64_tr_b16 v[88:89], v154 offset:33280
	v_pk_add_f32 v[250:251], v[250:251], v[92:93]
	v_pk_add_f32 v[250:251], v[250:251], v[94:95]
	v_cvt_pk_bf16_f32 v170, v90, v91
	v_cvt_pk_bf16_f32 v171, v92, v93
	s_waitcnt lgkmcnt(11)
	v_mfma_f32_32x32x16_bf16 v[114:129], v[198:201], v[186:189], v[114:129]
	ds_read_b64_tr_b16 v[90:91], v154 offset:36864
	ds_read_b64_tr_b16 v[92:93], v154 offset:37376
	s_waitcnt lgkmcnt(12)
	v_mfma_f32_32x32x16_bf16 v[98:113], v[142:145], v[186:189], v[98:113]
	v_pk_add_f32 v[250:251], v[250:251], v[96:97]
	v_pk_add_f32 v[250:251], v[250:251], v[66:67]
	v_cvt_pk_bf16_f32 v172, v94, v95
	v_cvt_pk_bf16_f32 v173, v96, v97
	s_nop 0
	v_pk_add_f32 v[250:251], v[250:251], v[68:69]
	v_pk_add_f32 v[250:251], v[250:251], v[70:71]
	v_cvt_pk_bf16_f32 v166, v66, v67
	v_cvt_pk_bf16_f32 v167, v68, v69
	s_waitcnt lgkmcnt(11)
	v_mfma_f32_32x32x16_bf16 v[114:129], v[194:197], v[182:185], v[114:129]
	s_waitcnt lgkmcnt(10)
	v_mfma_f32_32x32x16_bf16 v[98:113], v[134:137], v[182:185], v[98:113]
	v_pk_add_f32 v[250:251], v[250:251], v[72:73]
	v_pk_add_f32 v[250:251], v[250:251], v[74:75]
	v_cvt_pk_bf16_f32 v168, v70, v71
	v_cvt_pk_bf16_f32 v169, v72, v73
	s_nop 0
	v_pk_add_f32 v[250:251], v[250:251], v[76:77]
	v_pk_add_f32 v[250:251], v[250:251], v[78:79]
	v_cvt_pk_bf16_f32 v162, v74, v75
	v_cvt_pk_bf16_f32 v163, v76, v77
	s_waitcnt lgkmcnt(9)
	v_mfma_f32_32x32x16_bf16 v[114:129], v[138:141], v[178:181], v[114:129]
	s_waitcnt lgkmcnt(8)
	v_mfma_f32_32x32x16_bf16 v[98:113], v[130:133], v[178:181], v[98:113]
	v_pk_add_f32 v[250:251], v[250:251], v[80:81]
	v_cvt_pk_bf16_f32 v164, v78, v79
	v_cvt_pk_bf16_f32 v165, v80, v81
	s_lshl_b32 s12, s7, 13
	s_add_i32 s12, s12, s91
	v_add_f32_e32 v252, v250, v251
	v_add_f32_e32 v198, v202, v252
	v_lshl_add_u64 v[66:67], v[146:147], 0, s[24:25]
	s_mov_b32 s13, m0
	s_mov_b32 m0, s12
	s_nop 0
	global_load_lds_dwordx4 v[66:67], off
	s_mov_b32 m0, s13
	s_lshl_b32 s12, s0, 14
	v_lshl_add_u64 v[66:67], v[148:149], 0, s[4:5]
	s_add_i32 s12, s12, s92
	s_mov_b32 s13, m0
	s_mov_b32 m0, s12
	s_nop 0
	global_load_lds_dwordx4 v[66:67], off
	s_mov_b32 m0, s13
	v_lshl_add_u64 v[66:67], v[148:149], 0, s[8:9]
	s_addk_i32 s12, 0x2000
	s_mov_b32 s13, m0
	s_mov_b32 m0, s12
	s_nop 0
	global_load_lds_dwordx4 v[66:67], off
	s_mov_b32 m0, s13
	s_waitcnt lgkmcnt(6)
	v_mfma_f32_32x32x16_bf16 v[50:65], v[174:177], v[150:153], v[50:65]
	v_exp_f32_e32 v114, v114
	v_exp_f32_e32 v115, v115
	ds_read_b64_tr_b16 v[66:67], v154 offset:25600
	ds_read_b64_tr_b16 v[68:69], v154 offset:26112
	s_waitcnt lgkmcnt(6)
	v_mfma_f32_32x32x16_bf16 v[34:49], v[174:177], v[82:85], v[34:49]
	v_exp_f32_e32 v116, v116
	v_exp_f32_e32 v117, v117
	ds_read_b64_tr_b16 v[70:71], v154 offset:29696
	ds_read_b64_tr_b16 v[72:73], v154 offset:30208
	s_waitcnt lgkmcnt(6)
	v_mfma_f32_32x32x16_bf16 v[18:33], v[174:177], v[86:89], v[18:33]
	v_exp_f32_e32 v118, v118
	v_exp_f32_e32 v119, v119
	ds_read_b64_tr_b16 v[74:75], v154 offset:33792
	ds_read_b64_tr_b16 v[76:77], v154 offset:34304
	s_waitcnt lgkmcnt(6)
	v_mfma_f32_32x32x16_bf16 v[2:17], v[174:177], v[90:93], v[2:17]
	v_exp_f32_e32 v120, v120
	v_exp_f32_e32 v121, v121
	ds_read_b64_tr_b16 v[78:79], v154 offset:37888
	ds_read_b64_tr_b16 v[80:81], v154 offset:38400
	s_waitcnt lgkmcnt(6)
	v_mfma_f32_32x32x16_bf16 v[50:65], v[170:173], v[66:69], v[50:65]
	v_exp_f32_e32 v122, v122
	v_exp_f32_e32 v123, v123
	ds_read_b64_tr_b16 v[82:83], v154 offset:26624
	ds_read_b64_tr_b16 v[84:85], v154 offset:27136
	s_waitcnt lgkmcnt(6)
	v_mfma_f32_32x32x16_bf16 v[34:49], v[170:173], v[70:73], v[34:49]
	v_exp_f32_e32 v124, v124
	v_exp_f32_e32 v125, v125
	ds_read_b64_tr_b16 v[66:67], v154 offset:30720
	ds_read_b64_tr_b16 v[68:69], v154 offset:31232
	s_waitcnt lgkmcnt(6)
	v_mfma_f32_32x32x16_bf16 v[18:33], v[170:173], v[74:77], v[18:33]
	s_lshl_b32 s60, s0, 13
	v_exp_f32_e32 v126, v126
	v_exp_f32_e32 v127, v127
	v_add_u32_e32 v90, s60, v243
	ds_read_b128 v[70:73], v90
	ds_read_b128 v[130:133], v90 offset:512
	ds_read_b64_tr_b16 v[86:87], v154 offset:34816
	ds_read_b64_tr_b16 v[88:89], v154 offset:35328
	s_waitcnt lgkmcnt(8)
	v_mfma_f32_32x32x16_bf16 v[2:17], v[170:173], v[78:81], v[2:17]
	v_exp_f32_e32 v128, v128
	v_exp_f32_e32 v129, v129
	ds_read_b64_tr_b16 v[74:75], v154 offset:38912
	ds_read_b64_tr_b16 v[76:77], v154 offset:39424
	s_waitcnt lgkmcnt(8)
	v_mfma_f32_32x32x16_bf16 v[50:65], v[166:169], v[82:85], v[50:65]
	v_exp_f32_e32 v98, v98
	v_exp_f32_e32 v99, v99
	ds_read_b128 v[134:137], v90 offset:2048
	ds_read_b128 v[138:141], v90 offset:2560
	ds_read_b64_tr_b16 v[78:79], v154 offset:27648
	ds_read_b64_tr_b16 v[80:81], v154 offset:28160
	s_waitcnt lgkmcnt(10)
	v_mfma_f32_32x32x16_bf16 v[34:49], v[166:169], v[66:69], v[34:49]
	v_exp_f32_e32 v100, v100
	v_exp_f32_e32 v101, v101
	ds_read_b64_tr_b16 v[82:83], v154 offset:31744
	ds_read_b64_tr_b16 v[84:85], v154 offset:32256
	s_waitcnt lgkmcnt(8)
	v_mfma_f32_32x32x16_bf16 v[18:33], v[166:169], v[86:89], v[18:33]
	v_exp_f32_e32 v102, v102
	v_exp_f32_e32 v103, v103
	ds_read_b128 v[142:145], v90 offset:4096
	ds_read_b128 v[150:153], v90 offset:4608
	ds_read_b64_tr_b16 v[66:67], v154 offset:35840
	ds_read_b64_tr_b16 v[68:69], v154 offset:36352
	s_waitcnt lgkmcnt(10)
	v_mfma_f32_32x32x16_bf16 v[2:17], v[166:169], v[74:77], v[2:17]
	v_exp_f32_e32 v104, v104
	v_exp_f32_e32 v105, v105
	ds_read_b64_tr_b16 v[86:87], v154 offset:39936
	ds_read_b64_tr_b16 v[88:89], v154 offset:40448
	s_waitcnt lgkmcnt(8)
	v_mfma_f32_32x32x16_bf16 v[50:65], v[162:165], v[78:81], v[50:65]
	ds_read_b128 v[154:157], v90 offset:6144
	ds_read_b128 v[158:161], v90 offset:6656
	v_exp_f32_e32 v106, v106
	v_exp_f32_e32 v107, v107
	s_waitcnt lgkmcnt(8)
	v_mfma_f32_32x32x16_bf16 v[34:49], v[162:165], v[82:85], v[34:49]
	v_exp_f32_e32 v108, v108
	v_exp_f32_e32 v109, v109
	s_waitcnt lgkmcnt(4)
	v_mfma_f32_32x32x16_bf16 v[18:33], v[162:165], v[66:69], v[18:33]
	v_exp_f32_e32 v110, v110
	v_exp_f32_e32 v111, v111
	s_waitcnt lgkmcnt(2)
	v_mfma_f32_32x32x16_bf16 v[2:17], v[162:165], v[86:89], v[2:17]
	v_exp_f32_e32 v112, v112
	v_exp_f32_e32 v113, v113
	s_waitcnt vmcnt(3) lgkmcnt(0)
	s_barrier
; #define ATT_WAIT_BAR(N) asm volatile("s_waitcnt vmcnt(" #N ") lgkmcnt(0)\n\ts_barrier" ::: "memory")
; #define ROT() do { sl_prev = sl_cur; sl_cur = sl_next; sl_next = (sl_next == 2) ? 0 : sl_next + 1; } while (0)
; __device__ __forceinline__ void attn_unit(int b, int h, int qb, bool first, bool has_next, int nb, int nh, bf16_t* QO, const bf16_t* __restrict__ K, const bf16_t* __restrict__ V, float lam, char* shm) {
;     ...
;         int t = 1;
; #pragma unroll 1
;         for (; t + 1 <= NT - 4; t += 2) {
;             STEP(pB0, pB1, pA0, pA1, t, true, true, true);     ATT_WAIT_BAR(3); ROT();
;             STEP(pA0, pA1, pB0, pB1, t + 1, true, true, true); ATT_WAIT_BAR(3); ROT();
	s_add_i32 s12, s0, 1
	s_cmp_lg_u32 s0, 2
	s_cselect_b32 s33, s12, 0
	v_lshl_add_u32 v244, s7, 14, v241
	ds_read_b64_tr_b16 v[194:195], v244 offset:24576
	ds_read_b64_tr_b16 v[196:197], v244 offset:25088
	v_mfma_f32_32x32x16_bf16 v[82:97], v[70:73], v[190:193], 0
	v_pk_add_f32 v[250:251], v[114:115], v[116:117]
	v_pk_add_f32 v[250:251], v[250:251], v[118:119]
	v_cvt_pk_bf16_f32 v174, v114, v115
	v_cvt_pk_bf16_f32 v175, v116, v117
	ds_read_b64_tr_b16 v[114:115], v244 offset:28672
	ds_read_b64_tr_b16 v[116:117], v244 offset:29184
	v_pk_add_f32 v[250:251], v[250:251], v[120:121]
	v_pk_add_f32 v[250:251], v[250:251], v[122:123]
	v_mfma_f32_32x32x16_bf16 v[66:81], v[130:133], v[190:193], 0
	v_cvt_pk_bf16_f32 v176, v118, v119
	v_cvt_pk_bf16_f32 v177, v120, v121
	ds_read_b64_tr_b16 v[118:119], v244 offset:32768
	ds_read_b64_tr_b16 v[120:121], v244 offset:33280
	v_mfma_f32_32x32x16_bf16 v[82:97], v[134:137], v[186:189], v[82:97]
	v_pk_add_f32 v[250:251], v[250:251], v[124:125]
	v_pk_add_f32 v[250:251], v[250:251], v[126:127]
	v_cvt_pk_bf16_f32 v170, v122, v123
	v_cvt_pk_bf16_f32 v171, v124, v125
	ds_read_b64_tr_b16 v[122:123], v244 offset:36864
	ds_read_b64_tr_b16 v[124:125], v244 offset:37376
	v_mfma_f32_32x32x16_bf16 v[66:81], v[138:141], v[186:189], v[66:81]
	v_pk_add_f32 v[250:251], v[250:251], v[128:129]
	v_pk_add_f32 v[250:251], v[250:251], v[98:99]
	v_cvt_pk_bf16_f32 v172, v126, v127
	v_cvt_pk_bf16_f32 v173, v128, v129
	v_mfma_f32_32x32x16_bf16 v[82:97], v[142:145], v[182:185], v[82:97]
	v_pk_add_f32 v[250:251], v[250:251], v[100:101]
	v_pk_add_f32 v[250:251], v[250:251], v[102:103]
	v_cvt_pk_bf16_f32 v166, v98, v99
	v_cvt_pk_bf16_f32 v167, v100, v101
	v_mfma_f32_32x32x16_bf16 v[66:81], v[150:153], v[182:185], v[66:81]
	v_pk_add_f32 v[250:251], v[250:251], v[104:105]
	v_pk_add_f32 v[250:251], v[250:251], v[106:107]
	v_cvt_pk_bf16_f32 v168, v102, v103
	v_cvt_pk_bf16_f32 v169, v104, v105
	s_waitcnt lgkmcnt(9)
	v_mfma_f32_32x32x16_bf16 v[82:97], v[154:157], v[178:181], v[82:97]
	v_pk_add_f32 v[250:251], v[250:251], v[108:109]
	v_pk_add_f32 v[250:251], v[250:251], v[110:111]
	v_cvt_pk_bf16_f32 v162, v106, v107
	v_cvt_pk_bf16_f32 v163, v108, v109
	s_waitcnt lgkmcnt(8)
	v_mfma_f32_32x32x16_bf16 v[66:81], v[158:161], v[178:181], v[66:81]
	v_pk_add_f32 v[250:251], v[250:251], v[112:113]
	v_cvt_pk_bf16_f32 v164, v110, v111
	v_cvt_pk_bf16_f32 v165, v112, v113
	s_add_i32 s7, s60, s91
	v_add_f32_e32 v252, v250, v251
	v_add_f32_e32 v202, v198, v252
	v_lshl_add_u64 v[98:99], v[146:147], 0, s[30:31]
	s_mov_b32 s12, m0
	s_mov_b32 m0, s7
	s_nop 0
	global_load_lds_dwordx4 v[98:99], off
	s_mov_b32 m0, s12
	s_lshl_b32 s7, s33, 14
	v_lshl_add_u64 v[106:107], v[148:149], 0, s[22:23]
	s_add_i32 s7, s7, s92
	s_mov_b32 s12, m0
	s_mov_b32 m0, s7
	s_nop 0
	global_load_lds_dwordx4 v[106:107], off
	s_mov_b32 m0, s12
	v_lshl_add_u64 v[98:99], v[148:149], 0, s[44:45]
	s_addk_i32 s7, 0x2000
	s_mov_b32 s12, m0
	s_mov_b32 m0, s7
	s_nop 0
	global_load_lds_dwordx4 v[98:99], off
	s_mov_b32 m0, s12
	s_waitcnt lgkmcnt(6)
	v_mfma_f32_32x32x16_bf16 v[50:65], v[174:177], v[194:197], v[50:65]
	v_exp_f32_e32 v82, v82
	v_exp_f32_e32 v83, v83
	ds_read_b64_tr_b16 v[98:99], v244 offset:25600
	ds_read_b64_tr_b16 v[100:101], v244 offset:26112
	s_waitcnt lgkmcnt(6)
	v_mfma_f32_32x32x16_bf16 v[34:49], v[174:177], v[114:117], v[34:49]
	v_exp_f32_e32 v84, v84
	v_exp_f32_e32 v85, v85
	ds_read_b64_tr_b16 v[102:103], v244 offset:29696
	ds_read_b64_tr_b16 v[104:105], v244 offset:30208
	s_waitcnt lgkmcnt(6)
	v_mfma_f32_32x32x16_bf16 v[18:33], v[174:177], v[118:121], v[18:33]
	v_exp_f32_e32 v86, v86
	v_exp_f32_e32 v87, v87
	ds_read_b64_tr_b16 v[108:109], v244 offset:33792
	ds_read_b64_tr_b16 v[110:111], v244 offset:34304
	s_waitcnt lgkmcnt(6)
	v_mfma_f32_32x32x16_bf16 v[2:17], v[174:177], v[122:125], v[2:17]
	v_exp_f32_e32 v88, v88
	v_exp_f32_e32 v89, v89
	ds_read_b64_tr_b16 v[112:113], v244 offset:37888
	ds_read_b64_tr_b16 v[114:115], v244 offset:38400
	s_waitcnt lgkmcnt(6)
	v_mfma_f32_32x32x16_bf16 v[50:65], v[170:173], v[98:101], v[50:65]
	v_exp_f32_e32 v90, v90
	v_exp_f32_e32 v91, v91
	ds_read_b64_tr_b16 v[116:117], v244 offset:26624
	ds_read_b64_tr_b16 v[118:119], v244 offset:27136
	s_waitcnt lgkmcnt(6)
	v_mfma_f32_32x32x16_bf16 v[34:49], v[170:173], v[102:105], v[34:49]
	v_exp_f32_e32 v92, v92
	v_exp_f32_e32 v93, v93
	ds_read_b64_tr_b16 v[120:121], v244 offset:30720
	ds_read_b64_tr_b16 v[122:123], v244 offset:31232
	s_waitcnt lgkmcnt(6)
	v_mfma_f32_32x32x16_bf16 v[18:33], v[170:173], v[108:111], v[18:33]
	v_exp_f32_e32 v94, v94
	v_exp_f32_e32 v95, v95
	v_lshl_add_u32 v128, s33, 13, v243
	ds_read_b128 v[102:105], v128
	ds_read_b128 v[98:101], v128 offset:512
	ds_read_b64_tr_b16 v[124:125], v244 offset:34816
	ds_read_b64_tr_b16 v[126:127], v244 offset:35328
	s_waitcnt lgkmcnt(8)
	v_mfma_f32_32x32x16_bf16 v[2:17], v[170:173], v[112:115], v[2:17]
	v_exp_f32_e32 v96, v96
	v_exp_f32_e32 v97, v97
	ds_read_b64_tr_b16 v[108:109], v244 offset:38912
	ds_read_b64_tr_b16 v[110:111], v244 offset:39424
	s_waitcnt lgkmcnt(8)
	v_mfma_f32_32x32x16_bf16 v[50:65], v[166:169], v[116:119], v[50:65]
	v_exp_f32_e32 v66, v66
	v_exp_f32_e32 v67, v67
	ds_read_b128 v[198:201], v128 offset:2048
	ds_read_b128 v[142:145], v128 offset:2560
	ds_read_b64_tr_b16 v[112:113], v244 offset:27648
	ds_read_b64_tr_b16 v[114:115], v244 offset:28160
	s_waitcnt lgkmcnt(10)
	v_mfma_f32_32x32x16_bf16 v[34:49], v[166:169], v[120:123], v[34:49]
	v_exp_f32_e32 v68, v68
	v_exp_f32_e32 v69, v69
	ds_read_b64_tr_b16 v[116:117], v244 offset:31744
	ds_read_b64_tr_b16 v[118:119], v244 offset:32256
	s_waitcnt lgkmcnt(8)
	v_mfma_f32_32x32x16_bf16 v[18:33], v[166:169], v[124:127], v[18:33]
	v_exp_f32_e32 v70, v70
	v_exp_f32_e32 v71, v71
	ds_read_b128 v[194:197], v128 offset:4096
	ds_read_b128 v[134:137], v128 offset:4608
	ds_read_b64_tr_b16 v[120:121], v244 offset:35840
	ds_read_b64_tr_b16 v[122:123], v244 offset:36352
	s_waitcnt lgkmcnt(10)
	v_mfma_f32_32x32x16_bf16 v[2:17], v[166:169], v[108:111], v[2:17]
	v_exp_f32_e32 v72, v72
	v_exp_f32_e32 v73, v73
	ds_read_b64_tr_b16 v[124:125], v244 offset:39936
	ds_read_b64_tr_b16 v[126:127], v244 offset:40448
	s_waitcnt lgkmcnt(8)
	v_mfma_f32_32x32x16_bf16 v[50:65], v[162:165], v[112:115], v[50:65]
	ds_read_b128 v[138:141], v128 offset:6144
	ds_read_b128 v[130:133], v128 offset:6656
	v_exp_f32_e32 v74, v74
	v_exp_f32_e32 v75, v75
	s_waitcnt lgkmcnt(8)
	v_mfma_f32_32x32x16_bf16 v[34:49], v[162:165], v[116:119], v[34:49]
	v_exp_f32_e32 v76, v76
	v_exp_f32_e32 v77, v77
	s_waitcnt lgkmcnt(4)
	v_mfma_f32_32x32x16_bf16 v[18:33], v[162:165], v[120:123], v[18:33]
	v_exp_f32_e32 v78, v78
	v_exp_f32_e32 v79, v79
	s_waitcnt lgkmcnt(2)
	v_mfma_f32_32x32x16_bf16 v[2:17], v[162:165], v[124:127], v[2:17]
	v_exp_f32_e32 v80, v80
	v_exp_f32_e32 v81, v81
	s_add_i32 s12, s33, 1
	s_waitcnt vmcnt(3) lgkmcnt(0)
	s_barrier
; #define ATT_WAIT_BAR(N) asm volatile("s_waitcnt vmcnt(" #N ") lgkmcnt(0)\n\ts_barrier" ::: "memory")
; #define ROT() do { sl_prev = sl_cur; sl_cur = sl_next; sl_next = (sl_next == 2) ? 0 : sl_next + 1; } while (0)
; __device__ __forceinline__ void attn_unit(int b, int h, int qb, bool first, bool has_next, int nb, int nh, bf16_t* QO, const bf16_t* __restrict__ K, const bf16_t* __restrict__ V, float lam, char* shm) {
;     ...
;         int t = 1;
; #pragma unroll 1
;         for (; t + 1 <= NT - 4; t += 2) {
;             STEP(pB0, pB1, pA0, pA1, t, true, true, true);     ATT_WAIT_BAR(3); ROT();
;             STEP(pA0, pA1, pB0, pB1, t + 1, true, true, true); ATT_WAIT_BAR(3); ROT();
;         }
;         STEP(pB0, pB1, pA0, pA1, NT - 3, false, true, true);   ATT_WAIT_BAR(2); ROT();
	s_cmp_lg_u32 s33, 2
	s_mov_b32 s60, s0
	s_cselect_b32 s0, s12, 0
	s_add_i32 s6, s6, 2
	v_lshl_add_u64 v[146:147], v[146:147], 0, s[22:23]
	v_mov_b64_e32 v[148:149], v[106:107]
	s_mov_b32 s7, s33
	s_cmp_lt_u32 s6, 26
	s_cbranch_scc1 .LBB0_375
	ds_read_b64_tr_b16 v[106:107], v241 offset:40960
	ds_read_b64_tr_b16 v[108:109], v241 offset:41472
	v_add_f32_e32 v110, v82, v83
	v_add_f32_e32 v110, v84, v110
	v_add_f32_e32 v110, v85, v110
	v_add_f32_e32 v110, v86, v110
	v_add_f32_e32 v110, v87, v110
	v_cvt_pk_bf16_f32 v174, v82, v83
	v_cvt_pk_bf16_f32 v175, v84, v85
	v_mfma_f32_32x32x16_bf16 v[146:161], v[102:105], v[190:193], 0
	ds_read_b64_tr_b16 v[82:83], v241 offset:45056
	ds_read_b64_tr_b16 v[84:85], v241 offset:45568
	v_mfma_f32_32x32x16_bf16 v[114:129], v[98:101], v[190:193], 0
	v_add_f32_e32 v102, v88, v110
	v_add_f32_e32 v102, v89, v102
	v_add_f32_e32 v102, v90, v102
	v_add_f32_e32 v102, v91, v102
	v_cvt_pk_bf16_f32 v176, v86, v87
	v_cvt_pk_bf16_f32 v177, v88, v89
	ds_read_b64_tr_b16 v[86:87], v241 offset:49152
	ds_read_b64_tr_b16 v[88:89], v241 offset:49664
	v_add_f32_e32 v98, v92, v102
	v_add_f32_e32 v98, v93, v98
	v_add_f32_e32 v98, v94, v98
	v_add_f32_e32 v98, v95, v98
	v_cvt_pk_bf16_f32 v170, v90, v91
	v_cvt_pk_bf16_f32 v171, v92, v93
	v_mfma_f32_32x32x16_bf16 v[146:161], v[198:201], v[186:189], v[146:161]
	ds_read_b64_tr_b16 v[90:91], v241 offset:53248
	ds_read_b64_tr_b16 v[92:93], v241 offset:53760
	v_mfma_f32_32x32x16_bf16 v[114:129], v[142:145], v[186:189], v[114:129]
	v_add_f32_e32 v98, v96, v98
	v_add_f32_e32 v98, v97, v98
	v_add_f32_e32 v98, v66, v98
	v_add_f32_e32 v98, v67, v98
	v_cvt_pk_bf16_f32 v172, v94, v95
	v_cvt_pk_bf16_f32 v173, v96, v97
	s_nop 0
	v_add_f32_e32 v94, v68, v98
	v_add_f32_e32 v94, v69, v94
	v_add_f32_e32 v94, v70, v94
	v_add_f32_e32 v94, v71, v94
	v_cvt_pk_bf16_f32 v166, v66, v67
	v_cvt_pk_bf16_f32 v167, v68, v69
	v_mfma_f32_32x32x16_bf16 v[146:161], v[194:197], v[182:185], v[146:161]
	v_mfma_f32_32x32x16_bf16 v[114:129], v[134:137], v[182:185], v[114:129]
	v_add_f32_e32 v66, v72, v94
	v_add_f32_e32 v66, v73, v66
	v_add_f32_e32 v66, v74, v66
	v_add_f32_e32 v66, v75, v66
	v_cvt_pk_bf16_f32 v168, v70, v71
	v_cvt_pk_bf16_f32 v169, v72, v73
	s_nop 0
	v_add_f32_e32 v66, v76, v66
	v_add_f32_e32 v66, v77, v66
	v_add_f32_e32 v66, v78, v66
	v_add_f32_e32 v66, v79, v66
	v_cvt_pk_bf16_f32 v162, v74, v75
	v_cvt_pk_bf16_f32 v163, v76, v77
	s_waitcnt lgkmcnt(9)
	v_mfma_f32_32x32x16_bf16 v[146:161], v[138:141], v[178:181], v[146:161]
	s_waitcnt lgkmcnt(8)
	v_mfma_f32_32x32x16_bf16 v[114:129], v[130:133], v[178:181], v[114:129]
	v_add_f32_e32 v66, v80, v66
	v_add_f32_e32 v66, v81, v66
	v_add_f32_e32 v194, 0, v66
	v_cvt_pk_bf16_f32 v164, v78, v79
	v_cvt_pk_bf16_f32 v165, v80, v81
	s_mov_b32 s0, m0
	s_mov_b32 m0, s92
	s_nop 0
	global_load_lds_dwordx4 v[214:215], off
	s_mov_b32 m0, s0
	s_add_i32 s0, s92, 0x2000
	s_mov_b32 s6, m0
	s_mov_b32 m0, s0
	s_nop 0
	global_load_lds_dwordx4 v[216:217], off
	s_mov_b32 m0, s6
	s_waitcnt lgkmcnt(6)
	v_mfma_f32_32x32x16_bf16 v[50:65], v[174:177], v[106:109], v[50:65]
	s_nop 1
	v_exp_f32_e32 v146, v146
	v_exp_f32_e32 v147, v147
	ds_read_b64_tr_b16 v[66:67], v241 offset:41984
	ds_read_b64_tr_b16 v[68:69], v241 offset:42496
	s_waitcnt lgkmcnt(6)
	v_mfma_f32_32x32x16_bf16 v[34:49], v[174:177], v[82:85], v[34:49]
	v_exp_f32_e32 v148, v148
	v_exp_f32_e32 v149, v149
	ds_read_b64_tr_b16 v[70:71], v241 offset:46080
	ds_read_b64_tr_b16 v[72:73], v241 offset:46592
	s_waitcnt lgkmcnt(6)
	v_mfma_f32_32x32x16_bf16 v[18:33], v[174:177], v[86:89], v[18:33]
	v_exp_f32_e32 v150, v150
	v_exp_f32_e32 v151, v151
	ds_read_b64_tr_b16 v[74:75], v241 offset:50176
	ds_read_b64_tr_b16 v[76:77], v241 offset:50688
	s_waitcnt lgkmcnt(6)
	v_mfma_f32_32x32x16_bf16 v[2:17], v[174:177], v[90:93], v[2:17]
	v_exp_f32_e32 v152, v152
	v_exp_f32_e32 v153, v153
	ds_read_b64_tr_b16 v[78:79], v241 offset:54272
	ds_read_b64_tr_b16 v[80:81], v241 offset:54784
	s_waitcnt lgkmcnt(6)
	v_mfma_f32_32x32x16_bf16 v[50:65], v[170:173], v[66:69], v[50:65]
	v_exp_f32_e32 v154, v154
	v_exp_f32_e32 v155, v155
	ds_read_b64_tr_b16 v[82:83], v241 offset:43008
	ds_read_b64_tr_b16 v[84:85], v241 offset:43520
	s_waitcnt lgkmcnt(6)
	v_mfma_f32_32x32x16_bf16 v[34:49], v[170:173], v[70:73], v[34:49]
	v_exp_f32_e32 v156, v156
	v_exp_f32_e32 v157, v157
	ds_read_b64_tr_b16 v[66:67], v241 offset:47104
	ds_read_b64_tr_b16 v[68:69], v241 offset:47616
	s_waitcnt lgkmcnt(6)
	v_mfma_f32_32x32x16_bf16 v[18:33], v[170:173], v[74:77], v[18:33]
	v_exp_f32_e32 v158, v158
	v_exp_f32_e32 v159, v159
	ds_read_b128 v[70:73], v243
	ds_read_b128 v[86:89], v243 offset:512
	ds_read_b64_tr_b16 v[90:91], v241 offset:51200
	ds_read_b64_tr_b16 v[92:93], v241 offset:51712
	s_waitcnt lgkmcnt(8)
	v_mfma_f32_32x32x16_bf16 v[2:17], v[170:173], v[78:81], v[2:17]
	v_exp_f32_e32 v160, v160
	v_exp_f32_e32 v161, v161
	ds_read_b64_tr_b16 v[74:75], v241 offset:55296
	ds_read_b64_tr_b16 v[76:77], v241 offset:55808
	s_waitcnt lgkmcnt(8)
	v_mfma_f32_32x32x16_bf16 v[50:65], v[166:169], v[82:85], v[50:65]
	v_exp_f32_e32 v114, v114
	v_exp_f32_e32 v115, v115
	ds_read_b128 v[78:81], v243 offset:2048
	ds_read_b128 v[94:97], v243 offset:2560
	ds_read_b64_tr_b16 v[98:99], v241 offset:44032
	ds_read_b64_tr_b16 v[100:101], v241 offset:44544
	s_waitcnt lgkmcnt(10)
	v_mfma_f32_32x32x16_bf16 v[34:49], v[166:169], v[66:69], v[34:49]
	v_exp_f32_e32 v116, v116
	v_exp_f32_e32 v117, v117
	ds_read_b64_tr_b16 v[82:83], v241 offset:48128
	ds_read_b64_tr_b16 v[84:85], v241 offset:48640
	s_waitcnt lgkmcnt(8)
	v_mfma_f32_32x32x16_bf16 v[18:33], v[166:169], v[90:93], v[18:33]
	v_exp_f32_e32 v118, v118
	v_exp_f32_e32 v119, v119
	ds_read_b128 v[66:69], v243 offset:4096
	ds_read_b128 v[196:199], v243 offset:4608
	ds_read_b64_tr_b16 v[102:103], v241 offset:52224
	ds_read_b64_tr_b16 v[104:105], v241 offset:52736
	s_waitcnt lgkmcnt(10)
	v_mfma_f32_32x32x16_bf16 v[2:17], v[166:169], v[74:77], v[2:17]
	v_exp_f32_e32 v120, v120
	v_exp_f32_e32 v121, v121
	ds_read_b64_tr_b16 v[90:91], v241 offset:56320
	ds_read_b64_tr_b16 v[92:93], v241 offset:56832
	s_waitcnt lgkmcnt(8)
	v_mfma_f32_32x32x16_bf16 v[50:65], v[162:165], v[98:101], v[50:65]
	ds_read_b128 v[74:77], v243 offset:6144
	ds_read_b128 v[244:247], v243 offset:6656
	v_exp_f32_e32 v122, v122
	v_exp_f32_e32 v123, v123
	s_waitcnt lgkmcnt(8)
	v_mfma_f32_32x32x16_bf16 v[34:49], v[162:165], v[82:85], v[34:49]
	v_exp_f32_e32 v124, v124
	v_exp_f32_e32 v125, v125
	s_waitcnt lgkmcnt(4)
	v_mfma_f32_32x32x16_bf16 v[18:33], v[162:165], v[102:105], v[18:33]
	v_exp_f32_e32 v126, v126
	v_exp_f32_e32 v127, v127
	s_waitcnt lgkmcnt(2)
	v_mfma_f32_32x32x16_bf16 v[2:17], v[162:165], v[90:93], v[2:17]
	v_exp_f32_e32 v128, v128
	v_exp_f32_e32 v129, v129
	s_waitcnt vmcnt(2) lgkmcnt(0)
	s_barrier
; #define ATT_WAIT_BAR(N) asm volatile("s_waitcnt vmcnt(" #N ") lgkmcnt(0)\n\ts_barrier" ::: "memory")
; #define ROT() do { sl_prev = sl_cur; sl_cur = sl_next; sl_next = (sl_next == 2) ? 0 : sl_next + 1; } while (0)
; __device__ __forceinline__ void attn_unit(int b, int h, int qb, bool first, bool has_next, int nb, int nh, bf16_t* QO, const bf16_t* __restrict__ K, const bf16_t* __restrict__ V, float lam, char* shm) {
;     ...
;         int t = 1;
; #pragma unroll 1
;         for (; t + 1 <= NT - 4; t += 2) {
;             STEP(pB0, pB1, pA0, pA1, t, true, true, true);     ATT_WAIT_BAR(3); ROT();
;             STEP(pA0, pA1, pB0, pB1, t + 1, true, true, true); ATT_WAIT_BAR(3); ROT();
;         }
;         STEP(pB0, pB1, pA0, pA1, NT - 3, false, true, true);   ATT_WAIT_BAR(2); ROT();
;         STEP(pA0, pA1, pB0, pB1, NT - 2, false, true, true);   ATT_WAIT_BAR(0); ROT();
	ds_read_b64_tr_b16 v[82:83], v241 offset:57344
	ds_read_b64_tr_b16 v[84:85], v241 offset:57856
	v_add_f32_e32 v90, v146, v147
	v_add_f32_e32 v90, v148, v90
	v_add_f32_e32 v90, v149, v90
	v_add_f32_e32 v90, v150, v90
	v_add_f32_e32 v90, v151, v90
	v_cvt_pk_bf16_f32 v174, v146, v147
	v_cvt_pk_bf16_f32 v175, v148, v149
	v_mfma_f32_32x32x16_bf16 v[130:145], v[70:73], v[190:193], 0
	ds_read_b64_tr_b16 v[70:71], v241 offset:61440
	ds_read_b64_tr_b16 v[72:73], v241 offset:61952
	v_mfma_f32_32x32x16_bf16 v[98:113], v[86:89], v[190:193], 0
	v_add_f32_e32 v90, v152, v90
	v_add_f32_e32 v90, v153, v90
	v_add_f32_e32 v90, v154, v90
	v_add_f32_e32 v90, v155, v90
	v_cvt_pk_bf16_f32 v176, v150, v151
	v_cvt_pk_bf16_f32 v177, v152, v153
	ds_read_b64_tr_b16 v[86:87], v242 offset:40960
	ds_read_b64_tr_b16 v[88:89], v242 offset:41472
	v_add_f32_e32 v90, v156, v90
	v_add_f32_e32 v90, v157, v90
	v_add_f32_e32 v90, v158, v90
	v_add_f32_e32 v90, v159, v90
	v_cvt_pk_bf16_f32 v170, v154, v155
	v_cvt_pk_bf16_f32 v171, v156, v157
	v_mfma_f32_32x32x16_bf16 v[130:145], v[78:81], v[186:189], v[130:145]
	ds_read_b64_tr_b16 v[78:79], v242 offset:45056
	ds_read_b64_tr_b16 v[80:81], v242 offset:45568
	v_mfma_f32_32x32x16_bf16 v[98:113], v[94:97], v[186:189], v[98:113]
	v_add_f32_e32 v90, v160, v90
	v_add_f32_e32 v90, v161, v90
	v_add_f32_e32 v90, v114, v90
	v_add_f32_e32 v90, v115, v90
	v_cvt_pk_bf16_f32 v172, v158, v159
	v_cvt_pk_bf16_f32 v173, v160, v161
	s_nop 0
	v_add_f32_e32 v90, v116, v90
	v_add_f32_e32 v90, v117, v90
	v_add_f32_e32 v90, v118, v90
	v_add_f32_e32 v90, v119, v90
	v_cvt_pk_bf16_f32 v166, v114, v115
	v_cvt_pk_bf16_f32 v167, v116, v117
	v_mfma_f32_32x32x16_bf16 v[130:145], v[66:69], v[182:185], v[130:145]
	v_mfma_f32_32x32x16_bf16 v[98:113], v[196:199], v[182:185], v[98:113]
	v_add_f32_e32 v66, v120, v90
	v_add_f32_e32 v66, v121, v66
	v_add_f32_e32 v66, v122, v66
	v_add_f32_e32 v66, v123, v66
	v_cvt_pk_bf16_f32 v168, v118, v119
	v_cvt_pk_bf16_f32 v169, v120, v121
	s_nop 0
	v_add_f32_e32 v66, v124, v66
	v_add_f32_e32 v66, v125, v66
	v_add_f32_e32 v66, v126, v66
	v_add_f32_e32 v66, v127, v66
	v_cvt_pk_bf16_f32 v162, v122, v123
	v_cvt_pk_bf16_f32 v163, v124, v125
	s_waitcnt lgkmcnt(9)
	v_mfma_f32_32x32x16_bf16 v[130:145], v[74:77], v[178:181], v[130:145]
	s_waitcnt lgkmcnt(8)
	v_mfma_f32_32x32x16_bf16 v[98:113], v[244:247], v[178:181], v[98:113]
	v_add_f32_e32 v66, v128, v66
	v_add_f32_e32 v66, v129, v66
	v_add_f32_e32 v114, 0, v66
	v_cvt_pk_bf16_f32 v164, v126, v127
	v_cvt_pk_bf16_f32 v165, v128, v129
	s_cmp_lg_u32 0, -1
	s_cselect_b32 s0, 0, 0
	s_add_i32 s0, s0, s90
	s_add_i32 s6, s0, 0xa000
	s_mov_b32 s7, m0
	s_mov_b32 m0, s6
	s_nop 0
	global_load_lds_dwordx4 v[218:219], off
	s_mov_b32 m0, s7
	s_add_i32 s0, s0, 0xc000
	s_mov_b32 s6, m0
	s_mov_b32 m0, s0
	s_nop 0
	global_load_lds_dwordx4 v[220:221], off
	s_mov_b32 m0, s6
	s_waitcnt lgkmcnt(6)
	v_mfma_f32_32x32x16_bf16 v[50:65], v[174:177], v[82:85], v[50:65]
	v_exp_f32_e32 v130, v130
	v_exp_f32_e32 v131, v131
	ds_read_b64_tr_b16 v[66:67], v241 offset:58368
	ds_read_b64_tr_b16 v[68:69], v241 offset:58880
	s_waitcnt lgkmcnt(6)
	v_mfma_f32_32x32x16_bf16 v[34:49], v[174:177], v[70:73], v[34:49]
	v_exp_f32_e32 v132, v132
	v_exp_f32_e32 v133, v133
	ds_read_b64_tr_b16 v[74:75], v241 offset:62464
	ds_read_b64_tr_b16 v[76:77], v241 offset:62976
	s_waitcnt lgkmcnt(6)
	v_mfma_f32_32x32x16_bf16 v[18:33], v[174:177], v[86:89], v[18:33]
	v_exp_f32_e32 v134, v134
	v_exp_f32_e32 v135, v135
	ds_read_b64_tr_b16 v[70:71], v242 offset:41984
	ds_read_b64_tr_b16 v[72:73], v242 offset:42496
	s_waitcnt lgkmcnt(6)
	v_mfma_f32_32x32x16_bf16 v[2:17], v[174:177], v[78:81], v[2:17]
	v_exp_f32_e32 v136, v136
	v_exp_f32_e32 v137, v137
	ds_read_b64_tr_b16 v[82:83], v242 offset:46080
	ds_read_b64_tr_b16 v[84:85], v242 offset:46592
	s_waitcnt lgkmcnt(6)
	v_mfma_f32_32x32x16_bf16 v[50:65], v[170:173], v[66:69], v[50:65]
	v_exp_f32_e32 v138, v138
	v_exp_f32_e32 v139, v139
	ds_read_b64_tr_b16 v[78:79], v241 offset:59392
	ds_read_b64_tr_b16 v[80:81], v241 offset:59904
	s_waitcnt lgkmcnt(6)
	v_mfma_f32_32x32x16_bf16 v[34:49], v[170:173], v[74:77], v[34:49]
	v_exp_f32_e32 v140, v140
	v_exp_f32_e32 v141, v141
	ds_read_b64_tr_b16 v[66:67], v241 offset:63488
	ds_read_b64_tr_b16 v[68:69], v241 offset:64000
	s_waitcnt lgkmcnt(6)
	v_mfma_f32_32x32x16_bf16 v[18:33], v[170:173], v[70:73], v[18:33]
	v_exp_f32_e32 v142, v142
	v_exp_f32_e32 v143, v143
	ds_read_b128 v[74:77], v243 offset:8192
	ds_read_b128 v[86:89], v243 offset:8704
	ds_read_b64_tr_b16 v[90:91], v242 offset:43008
	ds_read_b64_tr_b16 v[92:93], v242 offset:43520
	s_waitcnt lgkmcnt(8)
	v_mfma_f32_32x32x16_bf16 v[2:17], v[170:173], v[82:85], v[2:17]
	v_exp_f32_e32 v144, v144
	v_exp_f32_e32 v145, v145
	ds_read_b64_tr_b16 v[70:71], v242 offset:47104
	ds_read_b64_tr_b16 v[72:73], v242 offset:47616
	s_waitcnt lgkmcnt(8)
	v_mfma_f32_32x32x16_bf16 v[50:65], v[166:169], v[78:81], v[50:65]
	v_exp_f32_e32 v98, v98
	v_exp_f32_e32 v99, v99
	ds_read_b128 v[116:119], v243 offset:10240
	ds_read_b128 v[120:123], v243 offset:10752
	ds_read_b64_tr_b16 v[82:83], v241 offset:60416
	ds_read_b64_tr_b16 v[84:85], v241 offset:60928
	s_waitcnt lgkmcnt(10)
	v_mfma_f32_32x32x16_bf16 v[34:49], v[166:169], v[66:69], v[34:49]
	v_exp_f32_e32 v100, v100
	v_exp_f32_e32 v101, v101
	ds_read_b64_tr_b16 v[78:79], v241 offset:64512
	ds_read_b64_tr_b16 v[80:81], v241 offset:65024
	s_waitcnt lgkmcnt(8)
	v_mfma_f32_32x32x16_bf16 v[18:33], v[166:169], v[90:93], v[18:33]
	v_exp_f32_e32 v102, v102
	v_exp_f32_e32 v103, v103
	ds_read_b128 v[124:127], v243 offset:12288
	ds_read_b128 v[146:149], v243 offset:12800
	ds_read_b64_tr_b16 v[66:67], v242 offset:44032
	ds_read_b64_tr_b16 v[68:69], v242 offset:44544
	s_waitcnt lgkmcnt(10)
	v_mfma_f32_32x32x16_bf16 v[2:17], v[166:169], v[70:73], v[2:17]
	v_exp_f32_e32 v104, v104
	v_exp_f32_e32 v105, v105
	ds_read_b64_tr_b16 v[90:91], v242 offset:48128
	ds_read_b64_tr_b16 v[92:93], v242 offset:48640
	s_waitcnt lgkmcnt(8)
	v_mfma_f32_32x32x16_bf16 v[50:65], v[162:165], v[82:85], v[50:65]
	ds_read_b128 v[150:153], v243 offset:14336
	ds_read_b128 v[154:157], v243 offset:14848
	v_exp_f32_e32 v106, v106
	v_exp_f32_e32 v107, v107
	s_waitcnt lgkmcnt(8)
	v_mfma_f32_32x32x16_bf16 v[34:49], v[162:165], v[78:81], v[34:49]
	v_exp_f32_e32 v108, v108
	v_exp_f32_e32 v109, v109
	s_waitcnt lgkmcnt(4)
	v_mfma_f32_32x32x16_bf16 v[18:33], v[162:165], v[66:69], v[18:33]
	v_exp_f32_e32 v110, v110
	v_exp_f32_e32 v111, v111
	s_waitcnt lgkmcnt(2)
	v_mfma_f32_32x32x16_bf16 v[2:17], v[162:165], v[90:93], v[2:17]
	v_exp_f32_e32 v112, v112
	v_exp_f32_e32 v113, v113
	s_waitcnt vmcnt(0) lgkmcnt(0)
	s_barrier
; #define ATT_WAIT_BAR(N) asm volatile("s_waitcnt vmcnt(" #N ") lgkmcnt(0)\n\ts_barrier" ::: "memory")
; #define ROT() do { sl_prev = sl_cur; sl_cur = sl_next; sl_next = (sl_next == 2) ? 0 : sl_next + 1; } while (0)
; __device__ __forceinline__ void attn_unit(int b, int h, int qb, bool first, bool has_next, int nb, int nh, bf16_t* QO, const bf16_t* __restrict__ K, const bf16_t* __restrict__ V, float lam, char* shm) {
;     ...
;         int t = 1;
; #pragma unroll 1
;         for (; t + 1 <= NT - 4; t += 2) {
;             STEP(pB0, pB1, pA0, pA1, t, true, true, true);     ATT_WAIT_BAR(3); ROT();
;             STEP(pA0, pA1, pB0, pB1, t + 1, true, true, true); ATT_WAIT_BAR(3); ROT();
;         }
;         STEP(pB0, pB1, pA0, pA1, NT - 3, false, true, true);   ATT_WAIT_BAR(2); ROT();
;         STEP(pA0, pA1, pB0, pB1, NT - 2, false, true, true);   ATT_WAIT_BAR(0); ROT();
;         STEP(pB0, pB1, pA0, pA1, NT - 1, false, false, false);
	ds_read_b64_tr_b16 v[158:159], v241 offset:24576
	ds_read_b64_tr_b16 v[160:161], v241 offset:25088
	v_add_f32_e32 v66, v130, v131
	v_add_f32_e32 v66, v132, v66
	v_add_f32_e32 v66, v133, v66
	v_add_f32_e32 v66, v134, v66
	v_add_f32_e32 v82, v135, v66
	v_mfma_f32_32x32x16_bf16 v[66:81], v[74:77], v[190:193], 0
	v_cvt_pk_bf16_f32 v174, v130, v131
	v_cvt_pk_bf16_f32 v175, v132, v133
	ds_read_b64_tr_b16 v[128:129], v241 offset:28672
	ds_read_b64_tr_b16 v[130:131], v241 offset:29184
	v_add_f32_e32 v82, v136, v82
	v_add_f32_e32 v82, v137, v82
	v_add_f32_e32 v82, v138, v82
	v_add_f32_e32 v115, v139, v82
	v_mfma_f32_32x32x16_bf16 v[82:97], v[86:89], v[190:193], 0
	v_cvt_pk_bf16_f32 v176, v134, v135
	v_cvt_pk_bf16_f32 v177, v136, v137
	ds_read_b64_tr_b16 v[132:133], v241 offset:32768
	ds_read_b64_tr_b16 v[134:135], v241 offset:33280
	v_mfma_f32_32x32x16_bf16 v[66:81], v[116:119], v[186:189], v[66:81]
	v_add_f32_e32 v115, v140, v115
	v_add_f32_e32 v115, v141, v115
	v_add_f32_e32 v115, v142, v115
	v_add_f32_e32 v115, v143, v115
	v_cvt_pk_bf16_f32 v170, v138, v139
	v_cvt_pk_bf16_f32 v171, v140, v141
	ds_read_b64_tr_b16 v[116:117], v241 offset:36864
	ds_read_b64_tr_b16 v[118:119], v241 offset:37376
	v_mfma_f32_32x32x16_bf16 v[82:97], v[120:123], v[186:189], v[82:97]
	v_add_f32_e32 v115, v144, v115
	v_add_f32_e32 v115, v145, v115
	v_add_f32_e32 v115, v98, v115
	v_add_f32_e32 v115, v99, v115
	v_cvt_pk_bf16_f32 v172, v142, v143
	v_cvt_pk_bf16_f32 v173, v144, v145
	v_mfma_f32_32x32x16_bf16 v[66:81], v[124:127], v[182:185], v[66:81]
	v_add_f32_e32 v115, v100, v115
	v_add_f32_e32 v115, v101, v115
	v_add_f32_e32 v115, v102, v115
	v_add_f32_e32 v115, v103, v115
	v_cvt_pk_bf16_f32 v166, v98, v99
	v_cvt_pk_bf16_f32 v167, v100, v101
	v_mfma_f32_32x32x16_bf16 v[82:97], v[146:149], v[182:185], v[82:97]
	v_add_f32_e32 v98, v104, v115
	v_add_f32_e32 v98, v105, v98
	v_add_f32_e32 v98, v106, v98
	v_add_f32_e32 v98, v107, v98
	v_cvt_pk_bf16_f32 v168, v102, v103
	v_cvt_pk_bf16_f32 v169, v104, v105
	s_waitcnt lgkmcnt(9)
	v_mfma_f32_32x32x16_bf16 v[66:81], v[150:153], v[178:181], v[66:81]
	v_add_f32_e32 v98, v108, v98
	v_add_f32_e32 v98, v109, v98
	v_add_f32_e32 v98, v110, v98
	v_add_f32_e32 v98, v111, v98
	v_cvt_pk_bf16_f32 v162, v106, v107
	v_cvt_pk_bf16_f32 v163, v108, v109
	s_waitcnt lgkmcnt(8)
	v_mfma_f32_32x32x16_bf16 v[82:97], v[154:157], v[178:181], v[82:97]
	v_add_f32_e32 v98, v112, v98
	v_add_f32_e32 v98, v113, v98
	v_add_f32_e32 v98, 0, v98
	v_cvt_pk_bf16_f32 v164, v110, v111
	v_cvt_pk_bf16_f32 v165, v112, v113
	s_waitcnt lgkmcnt(6)
	v_mfma_f32_32x32x16_bf16 v[50:65], v[174:177], v[158:161], v[50:65]
	v_exp_f32_e32 v66, v66
	v_exp_f32_e32 v67, v67
	ds_read_b64_tr_b16 v[100:101], v241 offset:25600
	ds_read_b64_tr_b16 v[102:103], v241 offset:26112
	s_waitcnt lgkmcnt(6)
	v_mfma_f32_32x32x16_bf16 v[34:49], v[174:177], v[128:131], v[34:49]
	v_exp_f32_e32 v68, v68
	v_exp_f32_e32 v69, v69
	ds_read_b64_tr_b16 v[104:105], v241 offset:29696
	ds_read_b64_tr_b16 v[106:107], v241 offset:30208
	s_waitcnt lgkmcnt(6)
	v_mfma_f32_32x32x16_bf16 v[18:33], v[174:177], v[132:135], v[18:33]
	v_exp_f32_e32 v70, v70
	v_exp_f32_e32 v71, v71
	ds_read_b64_tr_b16 v[108:109], v241 offset:33792
	ds_read_b64_tr_b16 v[110:111], v241 offset:34304
	s_waitcnt lgkmcnt(6)
	v_mfma_f32_32x32x16_bf16 v[2:17], v[174:177], v[116:119], v[2:17]
	v_exp_f32_e32 v72, v72
	v_exp_f32_e32 v73, v73
	ds_read_b64_tr_b16 v[120:121], v241 offset:37888
	ds_read_b64_tr_b16 v[122:123], v241 offset:38400
	s_waitcnt lgkmcnt(6)
	v_mfma_f32_32x32x16_bf16 v[50:65], v[170:173], v[100:103], v[50:65]
	v_exp_f32_e32 v74, v74
	v_exp_f32_e32 v75, v75
	ds_read_b64_tr_b16 v[116:117], v241 offset:26624
	ds_read_b64_tr_b16 v[118:119], v241 offset:27136
	s_waitcnt lgkmcnt(6)
	v_mfma_f32_32x32x16_bf16 v[34:49], v[170:173], v[104:107], v[34:49]
	v_exp_f32_e32 v76, v76
	v_exp_f32_e32 v77, v77
	ds_read_b64_tr_b16 v[100:101], v241 offset:30720
	ds_read_b64_tr_b16 v[102:103], v241 offset:31232
	s_waitcnt lgkmcnt(6)
	v_mfma_f32_32x32x16_bf16 v[18:33], v[170:173], v[108:111], v[18:33]
	v_exp_f32_e32 v78, v78
	v_exp_f32_e32 v79, v79
	ds_read_b64_tr_b16 v[104:105], v241 offset:34816
	ds_read_b64_tr_b16 v[106:107], v241 offset:35328
	s_waitcnt lgkmcnt(6)
	v_mfma_f32_32x32x16_bf16 v[2:17], v[170:173], v[120:123], v[2:17]
	v_exp_f32_e32 v80, v80
	v_exp_f32_e32 v81, v81
	ds_read_b64_tr_b16 v[108:109], v241 offset:38912
	ds_read_b64_tr_b16 v[110:111], v241 offset:39424
	s_waitcnt lgkmcnt(6)
	v_mfma_f32_32x32x16_bf16 v[50:65], v[166:169], v[116:119], v[50:65]
	v_exp_f32_e32 v82, v82
	v_exp_f32_e32 v83, v83
	ds_read_b64_tr_b16 v[120:121], v241 offset:27648
	ds_read_b64_tr_b16 v[122:123], v241 offset:28160
	s_waitcnt lgkmcnt(6)
	v_mfma_f32_32x32x16_bf16 v[34:49], v[166:169], v[100:103], v[34:49]
	v_exp_f32_e32 v84, v84
	v_exp_f32_e32 v85, v85
	ds_read_b64_tr_b16 v[116:117], v241 offset:31744
	ds_read_b64_tr_b16 v[118:119], v241 offset:32256
	s_waitcnt lgkmcnt(6)
	v_mfma_f32_32x32x16_bf16 v[18:33], v[166:169], v[104:107], v[18:33]
	v_exp_f32_e32 v86, v86
	v_exp_f32_e32 v87, v87
	ds_read_b64_tr_b16 v[100:101], v241 offset:35840
	ds_read_b64_tr_b16 v[102:103], v241 offset:36352
	s_waitcnt lgkmcnt(6)
	v_mfma_f32_32x32x16_bf16 v[2:17], v[166:169], v[108:111], v[2:17]
	v_exp_f32_e32 v88, v88
	v_exp_f32_e32 v89, v89
	ds_read_b64_tr_b16 v[104:105], v241 offset:39936
	ds_read_b64_tr_b16 v[106:107], v241 offset:40448
	s_waitcnt lgkmcnt(6)
; __device__ __forceinline__ void attn_unit(int b, int h, int qb, bool first, bool has_next, int nb, int nh, bf16_t* QO, const bf16_t* __restrict__ K, const bf16_t* __restrict__ V, float lam, char* shm) {
;     ...
;         int t = 1;
; #pragma unroll 1
;         for (; t + 1 <= NT - 4; t += 2) {
;             STEP(pB0, pB1, pA0, pA1, t, true, true, true);     ATT_WAIT_BAR(3); ROT();
;             STEP(pA0, pA1, pB0, pB1, t + 1, true, true, true); ATT_WAIT_BAR(3); ROT();
;         }
;         STEP(pB0, pB1, pA0, pA1, NT - 3, false, true, true);   ATT_WAIT_BAR(2); ROT();
;         STEP(pA0, pA1, pB0, pB1, NT - 2, false, true, true);   ATT_WAIT_BAR(0); ROT();
;         STEP(pB0, pB1, pA0, pA1, NT - 1, false, false, false);
;         { float sacc = pB0[0] + pB0[1];
; #pragma unroll
;           for (int r = 2; r < 16; ++r) sacc += pB0[r];
; #pragma unroll
;           for (int r = 0; r < 16; ++r) sacc += pB1[r];
;           l_reg += sacc;
;           pw0 = (u32x4){ATT_PK(pB0[0], pB0[1]), ATT_PK(pB0[2], pB0[3]), ATT_PK(pB0[4], pB0[5]), ATT_PK(pB0[6], pB0[7])};
;           pw1 = (u32x4){ATT_PK(pB0[8], pB0[9]), ATT_PK(pB0[10], pB0[11]), ATT_PK(pB0[12], pB0[13]), ATT_PK(pB0[14], pB0[15])};
;           pw2 = (u32x4){ATT_PK(pB1[0], pB1[1]), ATT_PK(pB1[2], pB1[3]), ATT_PK(pB1[4], pB1[5]), ATT_PK(pB1[6], pB1[7])};
;           pw3 = (u32x4){ATT_PK(pB1[8], pB1[9]), ATT_PK(pB1[10], pB1[11]), ATT_PK(pB1[12], pB1[13]), ATT_PK(pB1[14], pB1[15])};
;           ATT_SB();
;           const lds_cptr vp = vp0 + sl_cur * VSLOT;
; #pragma unroll
;           for (int d0 = 0; d0 < 4; ++d0) {
;               const s16x4 l0 = vtr(vp + d0 * 4096), h0 = vtr(vp + d0 * 4096 + 512), l1 = vtr(vp + d0 * 4096 + 1024), h1 = vtr(vp + d0 * 4096 + 1536);
;               const s16x4 l2 = vtr(vp + d0 * 4096 + 2048), h2 = vtr(vp + d0 * 4096 + 2560), l3 = vtr(vp + d0 * 4096 + 3072), h3 = vtr(vp + d0 * 4096 + 3584);
;               o[d0] = ATT_MFMA(PAF(0), ((bf16x8){l0[0], l0[1], l0[2], l0[3], h0[0], h0[1], h0[2], h0[3]}), o[d0]);
;               o[d0] = ATT_MFMA(PAF(1), ((bf16x8){l1[0], l1[1], l1[2], l1[3], h1[0], h1[1], h1[2], h1[3]}), o[d0]);
;               o[d0] = ATT_MFMA(PAF(2), ((bf16x8){l2[0], l2[1], l2[2], l2[3], h2[0], h2[1], h2[2], h2[3]}), o[d0]);
;               o[d0] = ATT_MFMA(PAF(3), ((bf16x8){l3[0], l3[1], l3[2], l3[3], h3[0], h3[1], h3[2], h3[3]}), o[d0]); } }
;     ...
;         ATT_SB();
	v_mfma_f32_32x32x16_bf16 v[50:65], v[162:165], v[120:123], v[50:65]
	v_exp_f32_e32 v90, v90
	v_exp_f32_e32 v91, v91
	s_waitcnt lgkmcnt(4)
	v_mfma_f32_32x32x16_bf16 v[34:49], v[162:165], v[116:119], v[34:49]
	v_exp_f32_e32 v92, v92
	v_exp_f32_e32 v93, v93
	s_waitcnt lgkmcnt(2)
	v_mfma_f32_32x32x16_bf16 v[18:33], v[162:165], v[100:103], v[18:33]
	v_exp_f32_e32 v94, v94
	v_exp_f32_e32 v95, v95
	s_waitcnt lgkmcnt(0)
	v_mfma_f32_32x32x16_bf16 v[2:17], v[162:165], v[104:107], v[2:17]
	v_exp_f32_e32 v96, v96
	v_exp_f32_e32 v97, v97
	v_cvt_pk_bf16_f32 v176, v70, v71
	v_cvt_pk_bf16_f32 v177, v72, v73
	v_cvt_pk_bf16_f32 v172, v78, v79
	v_cvt_pk_bf16_f32 v173, v80, v81
	v_cvt_pk_bf16_f32 v168, v86, v87
	v_cvt_pk_bf16_f32 v169, v88, v89
	v_cvt_pk_bf16_f32 v164, v94, v95
	v_cvt_pk_bf16_f32 v165, v96, v97
	v_cvt_pk_bf16_f32 v174, v66, v67
	v_cvt_pk_bf16_f32 v175, v68, v69
	v_cvt_pk_bf16_f32 v170, v74, v75
	v_cvt_pk_bf16_f32 v171, v76, v77
	v_cvt_pk_bf16_f32 v166, v82, v83
	v_cvt_pk_bf16_f32 v167, v84, v85
	v_cvt_pk_bf16_f32 v162, v90, v91
	v_cvt_pk_bf16_f32 v163, v92, v93
	ds_read_b64_tr_b16 v[100:101], v241 offset:40960
	ds_read_b64_tr_b16 v[102:103], v241 offset:41472
	ds_read_b64_tr_b16 v[104:105], v241 offset:41984
	ds_read_b64_tr_b16 v[106:107], v241 offset:42496
	s_waitcnt lgkmcnt(2)
	v_mfma_f32_32x32x16_bf16 v[50:65], v[174:177], v[100:103], v[50:65]
	s_waitcnt lgkmcnt(0)
	v_mfma_f32_32x32x16_bf16 v[50:65], v[170:173], v[104:107], v[50:65]
	ds_read_b64_tr_b16 v[100:101], v241 offset:43008
	ds_read_b64_tr_b16 v[102:103], v241 offset:43520
	ds_read_b64_tr_b16 v[104:105], v241 offset:44032
	ds_read_b64_tr_b16 v[106:107], v241 offset:44544
	s_waitcnt lgkmcnt(2)
	v_mfma_f32_32x32x16_bf16 v[50:65], v[166:169], v[100:103], v[50:65]
	s_waitcnt lgkmcnt(0)
	v_mfma_f32_32x32x16_bf16 v[50:65], v[162:165], v[104:107], v[50:65]
	ds_read_b64_tr_b16 v[100:101], v241 offset:45056
	ds_read_b64_tr_b16 v[102:103], v241 offset:45568
	ds_read_b64_tr_b16 v[104:105], v241 offset:46080
	ds_read_b64_tr_b16 v[106:107], v241 offset:46592
	s_waitcnt lgkmcnt(2)
	v_mfma_f32_32x32x16_bf16 v[34:49], v[174:177], v[100:103], v[34:49]
	s_waitcnt lgkmcnt(0)
	v_mfma_f32_32x32x16_bf16 v[34:49], v[170:173], v[104:107], v[34:49]
	ds_read_b64_tr_b16 v[100:101], v241 offset:47104
	ds_read_b64_tr_b16 v[102:103], v241 offset:47616
	ds_read_b64_tr_b16 v[104:105], v241 offset:48128
	ds_read_b64_tr_b16 v[106:107], v241 offset:48640
	s_waitcnt lgkmcnt(2)
	v_mfma_f32_32x32x16_bf16 v[34:49], v[166:169], v[100:103], v[34:49]
	s_waitcnt lgkmcnt(0)
	v_mfma_f32_32x32x16_bf16 v[34:49], v[162:165], v[104:107], v[34:49]
	ds_read_b64_tr_b16 v[100:101], v241 offset:49152
	ds_read_b64_tr_b16 v[102:103], v241 offset:49664
	ds_read_b64_tr_b16 v[104:105], v241 offset:50176
	ds_read_b64_tr_b16 v[106:107], v241 offset:50688
	s_waitcnt lgkmcnt(2)
	v_mfma_f32_32x32x16_bf16 v[18:33], v[174:177], v[100:103], v[18:33]
	s_waitcnt lgkmcnt(0)
	v_mfma_f32_32x32x16_bf16 v[18:33], v[170:173], v[104:107], v[18:33]
	ds_read_b64_tr_b16 v[100:101], v241 offset:51200
	ds_read_b64_tr_b16 v[102:103], v241 offset:51712
	ds_read_b64_tr_b16 v[104:105], v241 offset:52224
	ds_read_b64_tr_b16 v[106:107], v241 offset:52736
	s_waitcnt lgkmcnt(2)
	v_mfma_f32_32x32x16_bf16 v[18:33], v[166:169], v[100:103], v[18:33]
	s_waitcnt lgkmcnt(0)
	v_mfma_f32_32x32x16_bf16 v[18:33], v[162:165], v[104:107], v[18:33]
	ds_read_b64_tr_b16 v[100:101], v241 offset:53248
	ds_read_b64_tr_b16 v[102:103], v241 offset:53760
	ds_read_b64_tr_b16 v[104:105], v241 offset:54272
	ds_read_b64_tr_b16 v[106:107], v241 offset:54784
	s_waitcnt lgkmcnt(2)
	v_mfma_f32_32x32x16_bf16 v[2:17], v[174:177], v[100:103], v[2:17]
	s_waitcnt lgkmcnt(0)
	v_mfma_f32_32x32x16_bf16 v[2:17], v[170:173], v[104:107], v[2:17]
	ds_read_b64_tr_b16 v[100:101], v241 offset:55296
	ds_read_b64_tr_b16 v[102:103], v241 offset:55808
	ds_read_b64_tr_b16 v[104:105], v241 offset:56320
	ds_read_b64_tr_b16 v[106:107], v241 offset:56832
	s_waitcnt lgkmcnt(2)
	v_mfma_f32_32x32x16_bf16 v[2:17], v[166:169], v[100:103], v[2:17]
	s_waitcnt lgkmcnt(0)
	v_mfma_f32_32x32x16_bf16 v[2:17], v[162:165], v[104:107], v[2:17]
	s_waitcnt lgkmcnt(0)
	s_barrier
	s_or_b64 s[6:7], s[48:49], s[54:55]
	s_andn2_b64 vcc, exec, s[6:7]
	s_cbranch_vccnz .LBB0_378
	v_lshl_add_u64 v[100:101], v[232:233], 0, s[2:3]
	v_cndmask_b32_e64 v101, v223, v101, s[54:55]
	v_cndmask_b32_e64 v100, v222, v100, s[54:55]
	s_mov_b32 s0, m0
	s_mov_b32 m0, s91
	s_nop 0
	global_load_lds_dwordx4 v[100:101], off
	s_mov_b32 m0, s0
	v_cndmask_b32_e64 v103, v225, v205, s[54:55]
	v_cndmask_b32_e64 v102, v224, v204, s[54:55]
	s_mov_b32 s0, m0
	s_mov_b32 m0, s92
	s_nop 0
	global_load_lds_dwordx4 v[102:103], off
	s_mov_b32 m0, s0
	s_cmp_lg_u32 0, -1
	s_cselect_b32 s0, 0, 0
	s_add_i32 s0, s0, s90
	v_lshl_add_u64 v[102:103], v[102:103], 0, s[2:3]
	s_add_i32 s6, s0, 0x8000
	s_mov_b32 s7, m0
	s_mov_b32 m0, s6
	s_nop 0
	global_load_lds_dwordx4 v[102:103], off
	s_mov_b32 m0, s7
	v_lshl_add_u64 v[102:103], v[100:101], 0, s[4:5]
	s_add_i32 s6, s0, 0x2000
	s_mov_b32 s7, m0
	s_mov_b32 m0, s6
	s_nop 0
	global_load_lds_dwordx4 v[102:103], off
	s_mov_b32 m0, s7
	v_lshl_add_u64 v[100:101], v[100:101], 0, s[22:23]
	s_addk_i32 s0, 0x4000
	s_mov_b32 s6, m0
	s_mov_b32 m0, s0
	s_nop 0
	global_load_lds_dwordx4 v[100:101], off
	s_mov_b32 m0, s6

; __global__ void __launch_bounds__(512, 2) fwd_kernel(Args args) {
	.amdhsa_kernel _Z10fwd_kernel4Args
		.amdhsa_group_segment_fixed_size 0
		.amdhsa_private_segment_fixed_size 0
		.amdhsa_kernarg_size 432
		.amdhsa_user_sgpr_count 2
		.amdhsa_user_sgpr_dispatch_ptr 0
		.amdhsa_user_sgpr_queue_ptr 0
		.amdhsa_user_sgpr_kernarg_segment_ptr 1
		.amdhsa_user_sgpr_dispatch_id 0
		.amdhsa_user_sgpr_kernarg_preload_length 0
		.amdhsa_user_sgpr_kernarg_preload_offset 0
		.amdhsa_user_sgpr_private_segment_size 0
		.amdhsa_uses_dynamic_stack 0
		.amdhsa_enable_private_segment 0
		.amdhsa_system_sgpr_workgroup_id_x 1
		.amdhsa_system_sgpr_workgroup_id_y 0
		.amdhsa_system_sgpr_workgroup_id_z 0
		.amdhsa_system_sgpr_workgroup_info 0
		.amdhsa_system_vgpr_workitem_id 0
		.amdhsa_next_free_vgpr 256
		.amdhsa_next_free_sgpr 102
		.amdhsa_accum_offset 256
		.amdhsa_reserve_vcc 1
		.amdhsa_float_round_mode_32 0
		.amdhsa_float_round_mode_16_64 0
		.amdhsa_float_denorm_mode_32 3
		.amdhsa_float_denorm_mode_16_64 3
		.amdhsa_dx10_clamp 1
		.amdhsa_ieee_mode 1
		.amdhsa_fp16_overflow 0
		.amdhsa_tg_split 0
		.amdhsa_exception_fp_ieee_invalid_op 0
		.amdhsa_exception_fp_denorm_src 0
		.amdhsa_exception_fp_ieee_div_zero 0
		.amdhsa_exception_fp_ieee_overflow 0
		.amdhsa_exception_fp_ieee_underflow 0
		.amdhsa_exception_fp_ieee_inexact 0
		.amdhsa_exception_int_div_zero 0
	.end_amdhsa_kernel

; __global__ void __launch_bounds__(512, 2) fwd_kernel(Args args) {
amdhsa.kernels:
  - .agpr_count:     0
    .args:
      - .offset:         0
        .size:           176
        .value_kind:     by_value
      - .offset:         176
        .size:           4
        .value_kind:     hidden_block_count_x
      - .offset:         180
        .size:           4
        .value_kind:     hidden_block_count_y
      - .offset:         184
        .size:           4
        .value_kind:     hidden_block_count_z
      - .offset:         188
        .size:           2
        .value_kind:     hidden_group_size_x
      - .offset:         190
        .size:           2
        .value_kind:     hidden_group_size_y
      - .offset:         192
        .size:           2
        .value_kind:     hidden_group_size_z
      - .offset:         194
        .size:           2
        .value_kind:     hidden_remainder_x
      - .offset:         196
        .size:           2
        .value_kind:     hidden_remainder_y
      - .offset:         198
        .size:           2
        .value_kind:     hidden_remainder_z
      - .offset:         216
        .size:           8
        .value_kind:     hidden_global_offset_x
      - .offset:         224
        .size:           8
        .value_kind:     hidden_global_offset_y
      - .offset:         232
        .size:           8
        .value_kind:     hidden_global_offset_z
      - .offset:         240
        .size:           2
        .value_kind:     hidden_grid_dims
      - .offset:         296
        .size:           4
        .value_kind:     hidden_dynamic_lds_size
    .group_segment_fixed_size: 0
    .kernarg_segment_align: 8
    .kernarg_segment_size: 432
    .language:       OpenCL C
    .language_version:
      - 2
      - 0
    .max_flat_workgroup_size: 512
    .name:           _Z10fwd_kernel4Args
    .private_segment_fixed_size: 0
    .sgpr_count:     108
    .sgpr_spill_count: 22
    .symbol:         _Z10fwd_kernel4Args.kd
    .uniform_work_group_size: 1
    .uses_dynamic_stack: false
    .vgpr_count:     256
    .vgpr_spill_count: 0
    .wavefront_size: 64
